# mLSTM X1: both 8-MFMA K.V^T chains get their 16 LDS fragment reads issued 6 MFMAs ahead (counted waits), on top of the X3/SWA de-serialisation
# baseline (speedup 1.0000x reference)
; #define LAS __attribute__((address_space(3)))
; #define MFMA32(a, b, c) __builtin_amdgcn_mfma_f32_32x32x16_bf16((a), (b), (c), 0, 0, 0)
; DI unsigned cvtpk(float lo, float hi) { f32x2 v = {lo, hi}; bf16x2_t b = __builtin_convertvector(v, bf16x2_t); return __builtin_bit_cast(unsigned, b); }
; DI f32x16 zero16() { f32x16 z; for (int i = 0; i < 16; ++i) z[i] = 0.f; return z; }
; DI void mlstm_x1(const Params& p, LAS unsigned char* lds, int item, int tid_in, int lane_in, int wave) {
;     ...
;         for (int tile = wave; tile < 20; tile += 8) { const int td = tile & 3, te = tile >> 2;
;             f32x16 acc = zero16();
;             const LAS bf16* bp = VWTs + (te < 4 ? (32 * te + r) : 128) * MP + 8 * h; const LAS bf16* ap = KTs + (32 * td + r) * MP + 8 * h;
; #pragma unroll
;             for (int k0 = 0; k0 < 128; k0 += 16) acc = MFMA32(*(const LAS bf16x8*)(ap + k0), *(const LAS bf16x8*)(bp + k0), acc);
;             if (te < 4 || r == 0) { bf16* dst = Uo + (size_t)(te < 4 ? 32 * te + r : 128) * 128 + 32 * td + 4 * h;
; #pragma unroll
;                 for (int g = 0; g < 4; ++g) { u32x2 o; o.x = cvtpk(acc[4 * g], acc[4 * g + 1]); o.y = cvtpk(acc[4 * g + 2], acc[4 * g + 3]); *(u32x2*)(dst + 8 * g) = o; } } }
.LBB0_312:
	s_cmp_lt_u32 s9, 16
	s_cselect_b64 vcc, -1, 0
	s_and_b32 s0, s8, 0x60
	v_or_b32_e32 v0, s0, v28
	v_mad_u32_u24 v20, v0, s18, v30
	ds_read_b128 v[48:51], v20
	v_cndmask_b32_e32 v4, v17, v23, vcc
	v_lshl_add_u32 v33, v4, 1, v29
	ds_read_b128 v[52:55], v33 offset:35088
	ds_read_b128 v[56:59], v20 offset:32
	ds_read_b128 v[60:63], v33 offset:35120
	ds_read_b128 v[64:67], v20 offset:64
	ds_read_b128 v[68:71], v33 offset:35152
	s_or_b64 s[44:45], vcc, s[38:39]
	s_waitcnt lgkmcnt(4)
	v_mfma_f32_32x32x16_bf16 v[0:15], v[48:51], v[52:55], 0
	ds_read_b128 v[72:75], v20 offset:96
	ds_read_b128 v[76:79], v33 offset:35184
	s_waitcnt lgkmcnt(4)
	v_mfma_f32_32x32x16_bf16 v[0:15], v[56:59], v[60:63], v[0:15]
	ds_read_b128 v[80:83], v20 offset:128
	ds_read_b128 v[84:87], v33 offset:35216
	s_waitcnt lgkmcnt(4)
	v_mfma_f32_32x32x16_bf16 v[0:15], v[64:67], v[68:71], v[0:15]
	ds_read_b128 v[88:91], v20 offset:160
	ds_read_b128 v[92:95], v33 offset:35248
	s_waitcnt lgkmcnt(4)
	v_mfma_f32_32x32x16_bf16 v[0:15], v[72:75], v[76:79], v[0:15]
	ds_read_b128 v[96:99], v20 offset:192
	ds_read_b128 v[100:103], v33 offset:35280
	s_waitcnt lgkmcnt(4)
	v_mfma_f32_32x32x16_bf16 v[0:15], v[80:83], v[84:87], v[0:15]
	ds_read_b128 v[104:107], v20 offset:224
	ds_read_b128 v[108:111], v33 offset:35312
	s_waitcnt lgkmcnt(4)
	v_mfma_f32_32x32x16_bf16 v[0:15], v[88:91], v[92:95], v[0:15]
	s_waitcnt lgkmcnt(2)
	v_mfma_f32_32x32x16_bf16 v[0:15], v[96:99], v[100:103], v[0:15]
	s_waitcnt lgkmcnt(0)
	v_mfma_f32_32x32x16_bf16 v[0:15], v[104:107], v[108:111], v[0:15]
	s_and_saveexec_b64 s[6:7], s[44:45]
	s_cbranch_execz .LBB0_311
	v_cndmask_b32_e32 v35, 0, v25, vcc
	v_cndmask_b32_e32 v34, v26, v24, vcc
	v_lshl_add_u64 v[34:35], v[34:35], 1, s[4:5]
	s_lshl_b32 s0, s0, 1
	v_lshl_add_u64 v[34:35], v[34:35], 0, s[0:1]
	v_lshlrev_b32_e32 v20, 1, v31
	v_lshl_add_u64 v[34:35], v[34:35], 0, v[20:21]
	s_nop 2
	v_cvt_pk_bf16_f32 v0, v0, v1
	v_cvt_pk_bf16_f32 v1, v2, v3
	global_store_dwordx2 v[34:35], v[0:1], off
	v_cvt_pk_bf16_f32 v0, v4, v5
	v_cvt_pk_bf16_f32 v1, v6, v7
	global_store_dwordx2 v[34:35], v[0:1], off offset:16
	v_cvt_pk_bf16_f32 v0, v8, v9
	v_cvt_pk_bf16_f32 v1, v10, v11
	global_store_dwordx2 v[34:35], v[0:1], off offset:32
	v_cvt_pk_bf16_f32 v0, v12, v13
	v_cvt_pk_bf16_f32 v1, v14, v15
	global_store_dwordx2 v[34:35], v[0:1], off offset:48
	s_branch .LBB0_311

; #define LAS __attribute__((address_space(3)))
; #define MFMA32(a, b, c) __builtin_amdgcn_mfma_f32_32x32x16_bf16((a), (b), (c), 0, 0, 0)
; DI unsigned cvtpk(float lo, float hi) { f32x2 v = {lo, hi}; bf16x2_t b = __builtin_convertvector(v, bf16x2_t); return __builtin_bit_cast(unsigned, b); }
; DI f32x16 zero16() { f32x16 z; for (int i = 0; i < 16; ++i) z[i] = 0.f; return z; }
; DI void mlstm_x1(const Params& p, LAS unsigned char* lds, int item, int tid_in, int lane_in, int wave) {
;     ...
;         for (int tile = wave; tile < 20; tile += 8) { const int td = tile & 3, te = tile >> 2;
;             f32x16 acc = zero16();
;             const LAS bf16* bp = VWTs + (te < 4 ? (32 * te + r) : 128) * MP + 8 * h; const LAS bf16* ap = KTs + (32 * td + r) * MP + 8 * h;
; #pragma unroll
;             for (int k0 = 0; k0 < 128; k0 += 16) acc = MFMA32(*(const LAS bf16x8*)(ap + k0), *(const LAS bf16x8*)(bp + k0), acc);
;             if (te < 4 || r == 0) { bf16* dst = Uo + (size_t)(te < 4 ? 32 * te + r : 128) * 128 + 32 * td + 4 * h;
; #pragma unroll
;                 for (int g = 0; g < 4; ++g) { u32x2 o; o.x = cvtpk(acc[4 * g], acc[4 * g + 1]); o.y = cvtpk(acc[4 * g + 2], acc[4 * g + 3]); *(u32x2*)(dst + 8 * g) = o; } } }
.LBB0_322:
	s_cmp_lt_u32 s9, 16
	s_cselect_b64 vcc, -1, 0
	s_and_b32 s0, s8, 0x60
	v_or_b32_e32 v0, s0, v28
	v_mad_u32_u24 v20, v0, s18, v30
	ds_read_b128 v[48:51], v20
	v_cndmask_b32_e32 v4, v17, v24, vcc
	v_lshl_add_u32 v25, v4, 1, v29
	ds_read_b128 v[52:55], v25 offset:35088
	ds_read_b128 v[56:59], v20 offset:32
	ds_read_b128 v[60:63], v25 offset:35120
	ds_read_b128 v[64:67], v20 offset:64
	ds_read_b128 v[68:71], v25 offset:35152
	s_or_b64 s[36:37], vcc, s[38:39]
	s_waitcnt lgkmcnt(4)
	v_mfma_f32_32x32x16_bf16 v[0:15], v[48:51], v[52:55], 0
	ds_read_b128 v[72:75], v20 offset:96
	ds_read_b128 v[76:79], v25 offset:35184
	s_waitcnt lgkmcnt(4)
	v_mfma_f32_32x32x16_bf16 v[0:15], v[56:59], v[60:63], v[0:15]
	ds_read_b128 v[80:83], v20 offset:128
	ds_read_b128 v[84:87], v25 offset:35216
	s_waitcnt lgkmcnt(4)
	v_mfma_f32_32x32x16_bf16 v[0:15], v[64:67], v[68:71], v[0:15]
	ds_read_b128 v[88:91], v20 offset:160
	ds_read_b128 v[92:95], v25 offset:35248
	s_waitcnt lgkmcnt(4)
	v_mfma_f32_32x32x16_bf16 v[0:15], v[72:75], v[76:79], v[0:15]
	ds_read_b128 v[96:99], v20 offset:192
	ds_read_b128 v[100:103], v25 offset:35280
	s_waitcnt lgkmcnt(4)
	v_mfma_f32_32x32x16_bf16 v[0:15], v[80:83], v[84:87], v[0:15]
	ds_read_b128 v[104:107], v20 offset:224
	ds_read_b128 v[108:111], v25 offset:35312
	s_waitcnt lgkmcnt(4)
	v_mfma_f32_32x32x16_bf16 v[0:15], v[88:91], v[92:95], v[0:15]
	s_waitcnt lgkmcnt(2)
	v_mfma_f32_32x32x16_bf16 v[0:15], v[96:99], v[100:103], v[0:15]
	s_waitcnt lgkmcnt(0)
	v_mfma_f32_32x32x16_bf16 v[0:15], v[104:107], v[108:111], v[0:15]
	s_and_saveexec_b64 s[6:7], s[36:37]
	s_cbranch_execz .LBB0_321
	v_cndmask_b32_e32 v33, 0, v23, vcc
	v_cndmask_b32_e32 v32, v26, v22, vcc
	v_lshl_add_u64 v[32:33], v[32:33], 1, s[4:5]
	s_lshl_b32 s0, s0, 1
	v_lshl_add_u64 v[32:33], v[32:33], 0, s[0:1]
	v_lshlrev_b32_e32 v20, 1, v31
	v_lshl_add_u64 v[32:33], v[32:33], 0, v[20:21]
	s_nop 2
	v_cvt_pk_bf16_f32 v0, v0, v1
	v_cvt_pk_bf16_f32 v1, v2, v3
	global_store_dwordx2 v[32:33], v[0:1], off
	v_cvt_pk_bf16_f32 v0, v4, v5
	v_cvt_pk_bf16_f32 v1, v6, v7
	global_store_dwordx2 v[32:33], v[0:1], off offset:16
	v_cvt_pk_bf16_f32 v0, v8, v9
	v_cvt_pk_bf16_f32 v1, v10, v11
	global_store_dwordx2 v[32:33], v[0:1], off offset:32
	v_cvt_pk_bf16_f32 v0, v12, v13
	v_cvt_pk_bf16_f32 v1, v14, v15
	global_store_dwordx2 v[32:33], v[0:1], off offset:48
	s_branch .LBB0_321
